# v40 minus the 18 adjacent s_setprio 0 / s_setprio 1 pairs between the two MFMA blocks of each K-loop super-phase
# speedup vs baseline: 1.0049x; 1.0049x over previous
.LBB0_306:
	s_ashr_i32 s51, s50, 31
	s_lshl_b64 s[12:13], s[50:51], 19
	s_add_u32 s52, s8, s12
	s_addc_u32 s53, s9, s13
	s_and_b64 s[12:13], s[38:39], exec
	s_cselect_b32 s73, s53, s57
	s_cselect_b32 s74, s52, s56
	s_ashr_i32 s49, s48, 31
	s_lshl_b64 s[12:13], s[48:49], 19
	s_add_u32 s54, s2, s12
	s_addc_u32 s55, s16, s13
	s_and_b64 s[12:13], s[38:39], exec
	s_cselect_b32 s75, s55, s59
	s_cselect_b32 s76, s54, s58
	s_lshl_b64 s[12:13], s[50:51], 11
	v_lshl_add_u64 v[50:51], v[166:167], 0, s[12:13]
	s_lshl_b32 s12, s71, 12
	s_and_b32 s51, s12, 0x1000
	s_lshl_b64 s[12:13], s[48:49], 10
	s_add_u32 s56, s56, 0x40080
	s_addc_u32 s57, s57, 0
	v_lshl_add_u64 v[52:53], v[168:169], 0, s[12:13]
	s_add_u32 s12, s58, 0x100
	s_addc_u32 s13, s59, 0
	s_add_i32 s51, s23, s51
	s_mov_b32 s49, -2
	s_add_i32 s77, s51, 0x800
	s_mov_b64 s[58:59], 0
	s_add_u32 s60, s56, 0xfffc0080
	s_addc_u32 s61, s57, -1
	s_and_b64 s[58:59], s[58:59], exec
	s_cselect_b32 s61, s73, s61
	s_cselect_b32 s60, s74, s60
	s_cselect_b32 s59, s75, s13
	s_cselect_b32 s58, s76, s12
	s_add_i32 s80, 0, 0x10000
	s_add_i32 s82, 0, 0x14000
	v_add_u32_e32 v146, s80, v165
	v_add_u32_e32 v182, s82, v165
	ds_read_b128 v[54:57], v146
	ds_read_b128 v[66:69], v146 offset:1024
	ds_read_b128 v[70:73], v146 offset:2048
	ds_read_b128 v[146:149], v146 offset:3072
	ds_read_b128 v[150:153], v182
	ds_read_b128 v[174:177], v182 offset:1024
	ds_read_b128 v[178:181], v182 offset:2048
	ds_read_b128 v[182:185], v182 offset:3072
	v_lshl_add_u64 v[224:225], s[56:57], 0, v[170:171]
	s_add_i32 m0, s64, 0xc000
	ds_read_b128 v[190:193], v188
	ds_read_b128 v[194:197], v188 offset:1024
	ds_read_b128 v[198:201], v188 offset:2048
	ds_read_b128 v[202:205], v188 offset:3072
	ds_read_b128 v[208:211], v188 offset:4096
	ds_read_b128 v[212:215], v188 offset:5120
	ds_read_b128 v[216:219], v188 offset:6144
	ds_read_b128 v[220:223], v188 offset:7168
	global_load_lds_dwordx4 v[224:225], off
	v_lshl_add_u64 v[224:225], s[56:57], 0, v[172:173]
	s_add_i32 m0, s64, 0xe000
	s_nop 0
	global_load_lds_dwordx4 v[224:225], off
	s_waitcnt vmcnt(8)
	s_waitcnt lgkmcnt(0)
	s_barrier
	s_setprio 1
	s_waitcnt lgkmcnt(0)
	v_mfma_f32_16x16x32_bf16 v[142:145], v[54:57], v[190:193], 0
	v_mfma_f32_16x16x32_bf16 v[134:137], v[70:73], v[190:193], 0
	v_mfma_f32_16x16x32_bf16 v[126:129], v[54:57], v[198:201], 0
	v_mfma_f32_16x16x32_bf16 v[118:121], v[70:73], v[198:201], 0
	v_mfma_f32_16x16x32_bf16 v[110:113], v[54:57], v[208:211], 0
	v_mfma_f32_16x16x32_bf16 v[102:105], v[70:73], v[208:211], 0
	v_mfma_f32_16x16x32_bf16 v[94:97], v[54:57], v[216:219], 0
	v_mfma_f32_16x16x32_bf16 v[86:89], v[70:73], v[216:219], 0
	v_mfma_f32_16x16x32_bf16 v[142:145], v[66:69], v[194:197], v[142:145]
	v_mfma_f32_16x16x32_bf16 v[134:137], v[146:149], v[194:197], v[134:137]
	v_mfma_f32_16x16x32_bf16 v[126:129], v[66:69], v[202:205], v[126:129]
	v_mfma_f32_16x16x32_bf16 v[118:121], v[146:149], v[202:205], v[118:121]
	v_mfma_f32_16x16x32_bf16 v[110:113], v[66:69], v[212:215], v[110:113]
	v_mfma_f32_16x16x32_bf16 v[102:105], v[146:149], v[212:215], v[102:105]
	v_mfma_f32_16x16x32_bf16 v[94:97], v[66:69], v[220:223], v[94:97]
	v_mfma_f32_16x16x32_bf16 v[86:89], v[146:149], v[220:223], v[86:89]
	v_mfma_f32_16x16x32_bf16 v[138:141], v[150:153], v[190:193], 0
	v_mfma_f32_16x16x32_bf16 v[130:133], v[178:181], v[190:193], 0
	v_mfma_f32_16x16x32_bf16 v[122:125], v[150:153], v[198:201], 0
	v_mfma_f32_16x16x32_bf16 v[114:117], v[178:181], v[198:201], 0
	v_mfma_f32_16x16x32_bf16 v[106:109], v[150:153], v[208:211], 0
	v_mfma_f32_16x16x32_bf16 v[98:101], v[178:181], v[208:211], 0
	v_mfma_f32_16x16x32_bf16 v[90:93], v[150:153], v[216:219], 0
	v_mfma_f32_16x16x32_bf16 v[82:85], v[178:181], v[216:219], 0
	v_mfma_f32_16x16x32_bf16 v[138:141], v[174:177], v[194:197], v[138:141]
	v_mfma_f32_16x16x32_bf16 v[130:133], v[182:185], v[194:197], v[130:133]
	v_mfma_f32_16x16x32_bf16 v[122:125], v[174:177], v[202:205], v[122:125]
	v_mfma_f32_16x16x32_bf16 v[114:117], v[182:185], v[202:205], v[114:117]
	v_mfma_f32_16x16x32_bf16 v[106:109], v[174:177], v[212:215], v[106:109]
	v_mfma_f32_16x16x32_bf16 v[98:101], v[182:185], v[212:215], v[98:101]
	v_mfma_f32_16x16x32_bf16 v[90:93], v[174:177], v[220:223], v[90:93]
	v_mfma_f32_16x16x32_bf16 v[82:85], v[182:185], v[220:223], v[82:85]
	s_setprio 0
	s_barrier
	s_add_i32 s80, s80, s22
	v_lshl_add_u64 v[224:225], s[58:59], 0, v[158:159]
	s_mov_b32 m0, s80
	ds_read_b128 v[190:193], v188 offset:16384
	ds_read_b128 v[194:197], v188 offset:17408
	ds_read_b128 v[198:201], v188 offset:18432
	ds_read_b128 v[202:205], v188 offset:19456
	ds_read_b128 v[208:211], v188 offset:20480
	ds_read_b128 v[212:215], v188 offset:21504
	ds_read_b128 v[216:219], v188 offset:22528
	ds_read_b128 v[220:223], v188 offset:23552
	global_load_lds_dwordx4 v[224:225], off
	s_add_i32 m0, s80, 0x2000
	s_add_u32 s80, s58, 0x40000
	v_lshl_add_u64 v[226:227], s[58:59], 0, v[154:155]
	s_addc_u32 s81, s59, 0
	s_add_i32 s82, s82, s22
	global_load_lds_dwordx4 v[226:227], off
	v_lshl_add_u64 v[228:229], s[80:81], 0, v[158:159]
	s_mov_b32 m0, s82
	v_lshl_add_u64 v[230:231], s[60:61], 0, v[156:157]
	global_load_lds_dwordx4 v[228:229], off
	v_lshl_add_u64 v[228:229], s[80:81], 0, v[154:155]
	s_add_i32 m0, s82, 0x2000
	s_nop 0
	global_load_lds_dwordx4 v[228:229], off
	v_lshl_add_u64 v[228:229], s[60:61], 0, v[160:161]
	s_mov_b32 m0, s64
	s_nop 0
	global_load_lds_dwordx4 v[228:229], off
	s_mov_b32 m0, s65
	s_nop 0
	global_load_lds_dwordx4 v[230:231], off
	s_waitcnt vmcnt(8)
	s_waitcnt lgkmcnt(0)
	s_barrier
	s_setprio 1
	s_waitcnt lgkmcnt(0)
	v_mfma_f32_16x16x32_bf16 v[78:81], v[54:57], v[190:193], 0
	v_mfma_f32_16x16x32_bf16 v[62:65], v[70:73], v[190:193], 0
	v_mfma_f32_16x16x32_bf16 v[46:49], v[54:57], v[198:201], 0
	v_mfma_f32_16x16x32_bf16 v[38:41], v[70:73], v[198:201], 0
	v_mfma_f32_16x16x32_bf16 v[30:33], v[54:57], v[208:211], 0
	v_mfma_f32_16x16x32_bf16 v[22:25], v[70:73], v[208:211], 0
	v_mfma_f32_16x16x32_bf16 v[14:17], v[54:57], v[216:219], 0
	v_mfma_f32_16x16x32_bf16 v[6:9], v[70:73], v[216:219], 0
	v_mfma_f32_16x16x32_bf16 v[78:81], v[66:69], v[194:197], v[78:81]
	v_mfma_f32_16x16x32_bf16 v[62:65], v[146:149], v[194:197], v[62:65]
	v_mfma_f32_16x16x32_bf16 v[46:49], v[66:69], v[202:205], v[46:49]
	v_mfma_f32_16x16x32_bf16 v[38:41], v[146:149], v[202:205], v[38:41]
	v_mfma_f32_16x16x32_bf16 v[30:33], v[66:69], v[212:215], v[30:33]
	v_mfma_f32_16x16x32_bf16 v[22:25], v[146:149], v[212:215], v[22:25]
	v_mfma_f32_16x16x32_bf16 v[14:17], v[66:69], v[220:223], v[14:17]
	v_mfma_f32_16x16x32_bf16 v[6:9], v[146:149], v[220:223], v[6:9]
	v_mfma_f32_16x16x32_bf16 v[58:61], v[178:181], v[190:193], 0
	v_mfma_f32_16x16x32_bf16 v[42:45], v[150:153], v[198:201], 0
	v_mfma_f32_16x16x32_bf16 v[34:37], v[178:181], v[198:201], 0
	v_mfma_f32_16x16x32_bf16 v[26:29], v[150:153], v[208:211], 0
	v_mfma_f32_16x16x32_bf16 v[18:21], v[178:181], v[208:211], 0
	v_mfma_f32_16x16x32_bf16 v[10:13], v[150:153], v[216:219], 0
	v_mfma_f32_16x16x32_bf16 v[2:5], v[178:181], v[216:219], 0
	v_mfma_f32_16x16x32_bf16 v[54:57], v[150:153], v[190:193], 0
	v_mfma_f32_16x16x32_bf16 v[58:61], v[182:185], v[194:197], v[58:61]
	v_mfma_f32_16x16x32_bf16 v[42:45], v[174:177], v[202:205], v[42:45]
	v_mfma_f32_16x16x32_bf16 v[34:37], v[182:185], v[202:205], v[34:37]
	v_mfma_f32_16x16x32_bf16 v[26:29], v[174:177], v[212:215], v[26:29]
	v_mfma_f32_16x16x32_bf16 v[18:21], v[182:185], v[212:215], v[18:21]
	v_mfma_f32_16x16x32_bf16 v[10:13], v[174:177], v[220:223], v[10:13]
	v_mfma_f32_16x16x32_bf16 v[2:5], v[182:185], v[220:223], v[2:5]
	v_mfma_f32_16x16x32_bf16 v[54:57], v[174:177], v[194:197], v[54:57]
	s_setprio 0
	s_barrier
	s_branch .Lpeel_mid_sw
.LBB0_307:
	s_add_u32 s60, s56, 0xfffc0080
	s_addc_u32 s61, s57, -1
	s_and_b64 s[58:59], s[58:59], exec
	s_cselect_b32 s61, s73, s61
	s_cselect_b32 s60, s74, s60
	s_cselect_b32 s59, s75, s13
	s_cselect_b32 s58, s76, s12
	s_add_i32 s80, 0, 0x10000
	s_add_i32 s82, 0, 0x14000
	v_add_u32_e32 v146, s80, v165
	v_add_u32_e32 v182, s82, v165
	ds_read_b128 v[54:57], v146
	ds_read_b128 v[66:69], v146 offset:1024
	ds_read_b128 v[70:73], v146 offset:2048
	ds_read_b128 v[146:149], v146 offset:3072
	ds_read_b128 v[150:153], v182
	ds_read_b128 v[174:177], v182 offset:1024
	ds_read_b128 v[178:181], v182 offset:2048
	ds_read_b128 v[182:185], v182 offset:3072
	v_lshl_add_u64 v[224:225], s[56:57], 0, v[170:171]
	s_add_i32 m0, s64, 0xc000
	ds_read_b128 v[190:193], v188
	ds_read_b128 v[194:197], v188 offset:1024
	ds_read_b128 v[198:201], v188 offset:2048
	ds_read_b128 v[202:205], v188 offset:3072
	ds_read_b128 v[208:211], v188 offset:4096
	ds_read_b128 v[212:215], v188 offset:5120
	ds_read_b128 v[216:219], v188 offset:6144
	ds_read_b128 v[220:223], v188 offset:7168
	global_load_lds_dwordx4 v[224:225], off
	v_lshl_add_u64 v[224:225], s[56:57], 0, v[172:173]
	s_add_i32 m0, s64, 0xe000
	s_nop 0
	global_load_lds_dwordx4 v[224:225], off
	s_waitcnt vmcnt(8)
	s_waitcnt lgkmcnt(0)
	s_barrier
	s_setprio 1
	s_waitcnt lgkmcnt(0)
	v_mfma_f32_16x16x32_bf16 v[142:145], v[54:57], v[190:193], v[142:145]
	v_mfma_f32_16x16x32_bf16 v[134:137], v[70:73], v[190:193], v[134:137]
	v_mfma_f32_16x16x32_bf16 v[126:129], v[54:57], v[198:201], v[126:129]
	v_mfma_f32_16x16x32_bf16 v[118:121], v[70:73], v[198:201], v[118:121]
	v_mfma_f32_16x16x32_bf16 v[110:113], v[54:57], v[208:211], v[110:113]
	v_mfma_f32_16x16x32_bf16 v[102:105], v[70:73], v[208:211], v[102:105]
	v_mfma_f32_16x16x32_bf16 v[94:97], v[54:57], v[216:219], v[94:97]
	v_mfma_f32_16x16x32_bf16 v[86:89], v[70:73], v[216:219], v[86:89]
	v_mfma_f32_16x16x32_bf16 v[142:145], v[66:69], v[194:197], v[142:145]
	v_mfma_f32_16x16x32_bf16 v[134:137], v[146:149], v[194:197], v[134:137]
	v_mfma_f32_16x16x32_bf16 v[126:129], v[66:69], v[202:205], v[126:129]
	v_mfma_f32_16x16x32_bf16 v[118:121], v[146:149], v[202:205], v[118:121]
	v_mfma_f32_16x16x32_bf16 v[110:113], v[66:69], v[212:215], v[110:113]
	v_mfma_f32_16x16x32_bf16 v[102:105], v[146:149], v[212:215], v[102:105]
	v_mfma_f32_16x16x32_bf16 v[94:97], v[66:69], v[220:223], v[94:97]
	v_mfma_f32_16x16x32_bf16 v[86:89], v[146:149], v[220:223], v[86:89]
	v_mfma_f32_16x16x32_bf16 v[138:141], v[150:153], v[190:193], v[138:141]
	v_mfma_f32_16x16x32_bf16 v[130:133], v[178:181], v[190:193], v[130:133]
	v_mfma_f32_16x16x32_bf16 v[122:125], v[150:153], v[198:201], v[122:125]
	v_mfma_f32_16x16x32_bf16 v[114:117], v[178:181], v[198:201], v[114:117]
	v_mfma_f32_16x16x32_bf16 v[106:109], v[150:153], v[208:211], v[106:109]
	v_mfma_f32_16x16x32_bf16 v[98:101], v[178:181], v[208:211], v[98:101]
	v_mfma_f32_16x16x32_bf16 v[90:93], v[150:153], v[216:219], v[90:93]
	v_mfma_f32_16x16x32_bf16 v[82:85], v[178:181], v[216:219], v[82:85]
	v_mfma_f32_16x16x32_bf16 v[138:141], v[174:177], v[194:197], v[138:141]
	v_mfma_f32_16x16x32_bf16 v[130:133], v[182:185], v[194:197], v[130:133]
	v_mfma_f32_16x16x32_bf16 v[122:125], v[174:177], v[202:205], v[122:125]
	v_mfma_f32_16x16x32_bf16 v[114:117], v[182:185], v[202:205], v[114:117]
	v_mfma_f32_16x16x32_bf16 v[106:109], v[174:177], v[212:215], v[106:109]
	v_mfma_f32_16x16x32_bf16 v[98:101], v[182:185], v[212:215], v[98:101]
	v_mfma_f32_16x16x32_bf16 v[90:93], v[174:177], v[220:223], v[90:93]
	v_mfma_f32_16x16x32_bf16 v[82:85], v[182:185], v[220:223], v[82:85]
	s_setprio 0
	s_barrier
	s_add_i32 s80, s80, s22
	v_lshl_add_u64 v[224:225], s[58:59], 0, v[158:159]
	s_mov_b32 m0, s80
	ds_read_b128 v[190:193], v188 offset:16384
	ds_read_b128 v[194:197], v188 offset:17408
	ds_read_b128 v[198:201], v188 offset:18432
	ds_read_b128 v[202:205], v188 offset:19456
	ds_read_b128 v[208:211], v188 offset:20480
	ds_read_b128 v[212:215], v188 offset:21504
	ds_read_b128 v[216:219], v188 offset:22528
	ds_read_b128 v[220:223], v188 offset:23552
	global_load_lds_dwordx4 v[224:225], off
	s_add_i32 m0, s80, 0x2000
	s_add_u32 s80, s58, 0x40000
	v_lshl_add_u64 v[226:227], s[58:59], 0, v[154:155]
	s_addc_u32 s81, s59, 0
	s_add_i32 s82, s82, s22
	global_load_lds_dwordx4 v[226:227], off
	v_lshl_add_u64 v[228:229], s[80:81], 0, v[158:159]
	s_mov_b32 m0, s82
	v_lshl_add_u64 v[230:231], s[60:61], 0, v[156:157]
	global_load_lds_dwordx4 v[228:229], off
	v_lshl_add_u64 v[228:229], s[80:81], 0, v[154:155]
	s_add_i32 m0, s82, 0x2000
	s_nop 0
	global_load_lds_dwordx4 v[228:229], off
	v_lshl_add_u64 v[228:229], s[60:61], 0, v[160:161]
	s_mov_b32 m0, s64
	s_nop 0
	global_load_lds_dwordx4 v[228:229], off
	s_mov_b32 m0, s65
	s_nop 0
	global_load_lds_dwordx4 v[230:231], off
	s_waitcnt vmcnt(8)
	s_waitcnt lgkmcnt(0)
	s_barrier
	s_setprio 1
	s_waitcnt lgkmcnt(0)
	v_mfma_f32_16x16x32_bf16 v[78:81], v[54:57], v[190:193], v[78:81]
	v_mfma_f32_16x16x32_bf16 v[62:65], v[70:73], v[190:193], v[62:65]
	v_mfma_f32_16x16x32_bf16 v[46:49], v[54:57], v[198:201], v[46:49]
	v_mfma_f32_16x16x32_bf16 v[38:41], v[70:73], v[198:201], v[38:41]
	v_mfma_f32_16x16x32_bf16 v[30:33], v[54:57], v[208:211], v[30:33]
	v_mfma_f32_16x16x32_bf16 v[22:25], v[70:73], v[208:211], v[22:25]
	v_mfma_f32_16x16x32_bf16 v[14:17], v[54:57], v[216:219], v[14:17]
	v_mfma_f32_16x16x32_bf16 v[6:9], v[70:73], v[216:219], v[6:9]
	v_mfma_f32_16x16x32_bf16 v[78:81], v[66:69], v[194:197], v[78:81]
	v_mfma_f32_16x16x32_bf16 v[62:65], v[146:149], v[194:197], v[62:65]
	v_mfma_f32_16x16x32_bf16 v[46:49], v[66:69], v[202:205], v[46:49]
	v_mfma_f32_16x16x32_bf16 v[38:41], v[146:149], v[202:205], v[38:41]
	v_mfma_f32_16x16x32_bf16 v[30:33], v[66:69], v[212:215], v[30:33]
	v_mfma_f32_16x16x32_bf16 v[22:25], v[146:149], v[212:215], v[22:25]
	v_mfma_f32_16x16x32_bf16 v[14:17], v[66:69], v[220:223], v[14:17]
	v_mfma_f32_16x16x32_bf16 v[6:9], v[146:149], v[220:223], v[6:9]
	v_mfma_f32_16x16x32_bf16 v[58:61], v[178:181], v[190:193], v[58:61]
	v_mfma_f32_16x16x32_bf16 v[42:45], v[150:153], v[198:201], v[42:45]
	v_mfma_f32_16x16x32_bf16 v[34:37], v[178:181], v[198:201], v[34:37]
	v_mfma_f32_16x16x32_bf16 v[26:29], v[150:153], v[208:211], v[26:29]
	v_mfma_f32_16x16x32_bf16 v[18:21], v[178:181], v[208:211], v[18:21]
	v_mfma_f32_16x16x32_bf16 v[10:13], v[150:153], v[216:219], v[10:13]
	v_mfma_f32_16x16x32_bf16 v[2:5], v[178:181], v[216:219], v[2:5]
	v_mfma_f32_16x16x32_bf16 v[54:57], v[150:153], v[190:193], v[74:77]
	v_mfma_f32_16x16x32_bf16 v[58:61], v[182:185], v[194:197], v[58:61]
	v_mfma_f32_16x16x32_bf16 v[42:45], v[174:177], v[202:205], v[42:45]
	v_mfma_f32_16x16x32_bf16 v[34:37], v[182:185], v[202:205], v[34:37]
	v_mfma_f32_16x16x32_bf16 v[26:29], v[174:177], v[212:215], v[26:29]
	v_mfma_f32_16x16x32_bf16 v[18:21], v[182:185], v[212:215], v[18:21]
	v_mfma_f32_16x16x32_bf16 v[10:13], v[174:177], v[220:223], v[10:13]
	v_mfma_f32_16x16x32_bf16 v[2:5], v[182:185], v[220:223], v[2:5]
	v_mfma_f32_16x16x32_bf16 v[54:57], v[174:177], v[194:197], v[54:57]
	s_setprio 0
	s_barrier
.Lpeel_mid_sw:
	s_add_i32 s80, 0, 0x18000
	s_add_i32 s81, 0, 0x1c000
	v_add_u32_e32 v146, s80, v165
	v_add_u32_e32 v182, s81, v165
	ds_read_b128 v[66:69], v146
	ds_read_b128 v[70:73], v146 offset:1024
	ds_read_b128 v[74:77], v146 offset:2048
	ds_read_b128 v[146:149], v146 offset:3072
	ds_read_b128 v[150:153], v182
	ds_read_b128 v[174:177], v182 offset:1024
	ds_read_b128 v[178:181], v182 offset:2048
	ds_read_b128 v[182:185], v182 offset:3072
	s_add_u32 s60, s60, 0x40000
	s_addc_u32 s61, s61, 0
	s_mov_b32 m0, s66
	v_lshl_add_u64 v[232:233], s[60:61], 0, v[160:161]
	ds_read_b128 v[190:193], v188 offset:32768
	ds_read_b128 v[194:197], v188 offset:33792
	ds_read_b128 v[198:201], v188 offset:34816
	ds_read_b128 v[202:205], v188 offset:35840
	ds_read_b128 v[208:211], v188 offset:36864
	ds_read_b128 v[212:215], v188 offset:37888
	ds_read_b128 v[216:219], v188 offset:38912
	ds_read_b128 v[220:223], v188 offset:39936
	global_load_lds_dwordx4 v[232:233], off
	v_lshl_add_u64 v[232:233], s[60:61], 0, v[156:157]
	s_mov_b32 m0, s67
	s_nop 0
	global_load_lds_dwordx4 v[232:233], off
	s_waitcnt vmcnt(8)
	s_waitcnt lgkmcnt(0)
	s_barrier
	s_setprio 1
	s_waitcnt lgkmcnt(0)
	v_mfma_f32_16x16x32_bf16 v[142:145], v[66:69], v[190:193], v[142:145]
	v_mfma_f32_16x16x32_bf16 v[134:137], v[74:77], v[190:193], v[134:137]
	v_mfma_f32_16x16x32_bf16 v[126:129], v[66:69], v[198:201], v[126:129]
	v_mfma_f32_16x16x32_bf16 v[118:121], v[74:77], v[198:201], v[118:121]
	v_mfma_f32_16x16x32_bf16 v[110:113], v[66:69], v[208:211], v[110:113]
	v_mfma_f32_16x16x32_bf16 v[102:105], v[74:77], v[208:211], v[102:105]
	v_mfma_f32_16x16x32_bf16 v[94:97], v[66:69], v[216:219], v[94:97]
	v_mfma_f32_16x16x32_bf16 v[86:89], v[74:77], v[216:219], v[86:89]
	v_mfma_f32_16x16x32_bf16 v[142:145], v[70:73], v[194:197], v[142:145]
	v_mfma_f32_16x16x32_bf16 v[134:137], v[146:149], v[194:197], v[134:137]
	v_mfma_f32_16x16x32_bf16 v[126:129], v[70:73], v[202:205], v[126:129]
	v_mfma_f32_16x16x32_bf16 v[118:121], v[146:149], v[202:205], v[118:121]
	v_mfma_f32_16x16x32_bf16 v[110:113], v[70:73], v[212:215], v[110:113]
	v_mfma_f32_16x16x32_bf16 v[102:105], v[146:149], v[212:215], v[102:105]
	v_mfma_f32_16x16x32_bf16 v[94:97], v[70:73], v[220:223], v[94:97]
	v_mfma_f32_16x16x32_bf16 v[86:89], v[146:149], v[220:223], v[86:89]
	v_mfma_f32_16x16x32_bf16 v[138:141], v[150:153], v[190:193], v[138:141]
	v_mfma_f32_16x16x32_bf16 v[130:133], v[178:181], v[190:193], v[130:133]
	v_mfma_f32_16x16x32_bf16 v[122:125], v[150:153], v[198:201], v[122:125]
	v_mfma_f32_16x16x32_bf16 v[114:117], v[178:181], v[198:201], v[114:117]
	v_mfma_f32_16x16x32_bf16 v[106:109], v[150:153], v[208:211], v[106:109]
	v_mfma_f32_16x16x32_bf16 v[98:101], v[178:181], v[208:211], v[98:101]
	v_mfma_f32_16x16x32_bf16 v[90:93], v[150:153], v[216:219], v[90:93]
	v_mfma_f32_16x16x32_bf16 v[82:85], v[178:181], v[216:219], v[82:85]
	v_mfma_f32_16x16x32_bf16 v[138:141], v[174:177], v[194:197], v[138:141]
	v_mfma_f32_16x16x32_bf16 v[130:133], v[182:185], v[194:197], v[130:133]
	v_mfma_f32_16x16x32_bf16 v[122:125], v[174:177], v[202:205], v[122:125]
	v_mfma_f32_16x16x32_bf16 v[114:117], v[182:185], v[202:205], v[114:117]
	v_mfma_f32_16x16x32_bf16 v[106:109], v[174:177], v[212:215], v[106:109]
	v_mfma_f32_16x16x32_bf16 v[98:101], v[182:185], v[212:215], v[98:101]
	v_mfma_f32_16x16x32_bf16 v[90:93], v[174:177], v[220:223], v[90:93]
	v_mfma_f32_16x16x32_bf16 v[82:85], v[182:185], v[220:223], v[82:85]
	s_setprio 0
	s_barrier
	s_add_i32 s60, s80, s22
	v_lshl_add_u64 v[224:225], v[224:225], 0, s[0:1]
	s_mov_b32 m0, s60
	ds_read_b128 v[190:193], v188 offset:49152
	ds_read_b128 v[194:197], v188 offset:50176
	ds_read_b128 v[198:201], v188 offset:51200
	ds_read_b128 v[202:205], v188 offset:52224
	ds_read_b128 v[208:211], v188 offset:53248
	ds_read_b128 v[212:215], v188 offset:54272
	ds_read_b128 v[216:219], v188 offset:55296
	ds_read_b128 v[220:223], v188 offset:56320
	global_load_lds_dwordx4 v[224:225], off
	s_add_i32 m0, s60, 0x2000
	s_add_u32 s58, s58, 0x40080
	v_lshl_add_u64 v[224:225], v[226:227], 0, s[0:1]
	s_addc_u32 s59, s59, 0
	s_add_i32 s60, s81, s22
	global_load_lds_dwordx4 v[224:225], off
	v_lshl_add_u64 v[224:225], s[58:59], 0, v[158:159]
	s_mov_b32 m0, s60
	s_nop 0
	global_load_lds_dwordx4 v[224:225], off
	v_lshl_add_u64 v[224:225], s[58:59], 0, v[154:155]
	s_add_i32 m0, s60, 0x2000
	s_nop 0
	global_load_lds_dwordx4 v[224:225], off
	v_lshl_add_u64 v[224:225], v[228:229], 0, s[0:1]
	s_mov_b32 m0, s69
	s_nop 0
	global_load_lds_dwordx4 v[224:225], off
	v_lshl_add_u64 v[224:225], v[230:231], 0, s[0:1]
	s_mov_b32 m0, s70
	s_nop 0
	global_load_lds_dwordx4 v[224:225], off
	s_waitcnt vmcnt(8)
	s_waitcnt lgkmcnt(0)
	s_barrier
	s_setprio 1
	s_waitcnt lgkmcnt(0)
	v_mfma_f32_16x16x32_bf16 v[78:81], v[66:69], v[190:193], v[78:81]
	v_mfma_f32_16x16x32_bf16 v[62:65], v[74:77], v[190:193], v[62:65]
	v_mfma_f32_16x16x32_bf16 v[46:49], v[66:69], v[198:201], v[46:49]
	v_mfma_f32_16x16x32_bf16 v[38:41], v[74:77], v[198:201], v[38:41]
	v_mfma_f32_16x16x32_bf16 v[30:33], v[66:69], v[208:211], v[30:33]
	v_mfma_f32_16x16x32_bf16 v[22:25], v[74:77], v[208:211], v[22:25]
	v_mfma_f32_16x16x32_bf16 v[14:17], v[66:69], v[216:219], v[14:17]
	v_mfma_f32_16x16x32_bf16 v[6:9], v[74:77], v[216:219], v[6:9]
	v_mfma_f32_16x16x32_bf16 v[78:81], v[70:73], v[194:197], v[78:81]
	v_mfma_f32_16x16x32_bf16 v[62:65], v[146:149], v[194:197], v[62:65]
	v_mfma_f32_16x16x32_bf16 v[46:49], v[70:73], v[202:205], v[46:49]
	v_mfma_f32_16x16x32_bf16 v[38:41], v[146:149], v[202:205], v[38:41]
	v_mfma_f32_16x16x32_bf16 v[30:33], v[70:73], v[212:215], v[30:33]
	v_mfma_f32_16x16x32_bf16 v[22:25], v[146:149], v[212:215], v[22:25]
	v_mfma_f32_16x16x32_bf16 v[14:17], v[70:73], v[220:223], v[14:17]
	v_mfma_f32_16x16x32_bf16 v[6:9], v[146:149], v[220:223], v[6:9]
	v_mfma_f32_16x16x32_bf16 v[54:57], v[150:153], v[190:193], v[54:57]
	v_mfma_f32_16x16x32_bf16 v[74:77], v[174:177], v[194:197], v[54:57]
	v_mfma_f32_16x16x32_bf16 v[54:57], v[178:181], v[190:193], v[58:61]
	v_mfma_f32_16x16x32_bf16 v[42:45], v[150:153], v[198:201], v[42:45]
	v_mfma_f32_16x16x32_bf16 v[34:37], v[178:181], v[198:201], v[34:37]
	v_mfma_f32_16x16x32_bf16 v[26:29], v[150:153], v[208:211], v[26:29]
	v_mfma_f32_16x16x32_bf16 v[18:21], v[178:181], v[208:211], v[18:21]
	v_mfma_f32_16x16x32_bf16 v[10:13], v[150:153], v[216:219], v[10:13]
	v_mfma_f32_16x16x32_bf16 v[2:5], v[178:181], v[216:219], v[2:5]
	v_mfma_f32_16x16x32_bf16 v[58:61], v[182:185], v[194:197], v[54:57]
	v_mfma_f32_16x16x32_bf16 v[42:45], v[174:177], v[202:205], v[42:45]
	v_mfma_f32_16x16x32_bf16 v[34:37], v[182:185], v[202:205], v[34:37]
	v_mfma_f32_16x16x32_bf16 v[26:29], v[174:177], v[212:215], v[26:29]
	v_mfma_f32_16x16x32_bf16 v[18:21], v[182:185], v[212:215], v[18:21]
	v_mfma_f32_16x16x32_bf16 v[10:13], v[174:177], v[220:223], v[10:13]
	v_mfma_f32_16x16x32_bf16 v[2:5], v[182:185], v[220:223], v[2:5]
	s_setprio 0
	s_barrier
	s_add_i32 s49, s49, 2
	s_add_u32 s56, s56, 0x100
	s_addc_u32 s57, s57, 0
	s_add_u32 s12, s12, 0x100
	s_addc_u32 s13, s13, 0
	s_cmp_gt_u32 s49, 13
	s_cbranch_scc1 .LBB0_310

.LBB0_387:
	s_ashr_i32 s65, s64, 31
	s_lshl_b64 s[12:13], s[64:65], 11
	v_lshl_add_u64 v[130:131], v[174:175], 0, s[12:13]
	s_lshl_b32 s12, s57, 12
	s_add_i32 s69, s90, -2
	s_and_b32 s65, s12, 0x1000
	s_lshl_b64 s[12:13], s[66:67], 10
	s_add_u32 s74, s74, 0x80
	s_addc_u32 s75, s75, 0
	s_add_u32 s67, s76, 0x100
	s_waitcnt lgkmcnt(0)
	v_lshl_add_u64 v[132:133], v[176:177], 0, s[12:13]
	s_addc_u32 s73, s77, 0
	s_mov_b32 s12, 0
	s_mov_b64 s[76:77], 0
	s_add_i32 s12, s12, 2
	s_add_u32 s13, s74, 0x80
	s_addc_u32 vcc_lo, s75, 0
	s_and_b64 s[76:77], s[76:77], exec
	s_cselect_b32 s77, s71, vcc_lo
	s_cselect_b32 s76, s70, s13
	s_cselect_b32 vcc_hi, s45, s73
	s_cselect_b32 vcc_lo, s44, s67
	s_add_i32 s13, 0, 0x10000
	v_add_u32_e32 v1, s13, v208
	s_add_i32 s88, 0, 0x14000
	ds_read_b128 v[134:137], v1
	ds_read_b128 v[138:141], v1 offset:1024
	ds_read_b128 v[142:145], v1 offset:2048
	ds_read_b128 v[146:149], v1 offset:3072
	v_add_u32_e32 v1, s88, v208
	ds_read_b128 v[150:153], v1
	ds_read_b128 v[154:157], v1 offset:1024
	ds_read_b128 v[158:161], v1 offset:2048
	ds_read_b128 v[182:185], v1 offset:3072
	v_lshl_add_u64 v[224:225], s[74:75], 0, v[178:179]
	s_add_i32 m0, s80, 0xc000
	ds_read_b128 v[186:189], v211
	ds_read_b128 v[190:193], v211 offset:1024
	ds_read_b128 v[194:197], v211 offset:2048
	ds_read_b128 v[198:201], v211 offset:3072
	ds_read_b128 v[202:205], v211 offset:4096
	ds_read_b128 v[212:215], v211 offset:5120
	ds_read_b128 v[216:219], v211 offset:6144
	ds_read_b128 v[220:223], v211 offset:7168
	global_load_lds_dwordx4 v[224:225], off
	v_lshl_add_u64 v[224:225], s[74:75], 0, v[180:181]
	s_add_i32 m0, s80, 0xe000
	s_nop 0
	global_load_lds_dwordx4 v[224:225], off
	s_waitcnt vmcnt(8)
	s_waitcnt lgkmcnt(0)
	s_barrier
	s_setprio 1
	s_waitcnt lgkmcnt(0)
	v_mfma_f32_16x16x32_bf16 v[126:129], v[134:137], v[186:189], 0
	v_mfma_f32_16x16x32_bf16 v[122:125], v[142:145], v[186:189], 0
	v_mfma_f32_16x16x32_bf16 v[118:121], v[134:137], v[194:197], 0
	v_mfma_f32_16x16x32_bf16 v[114:117], v[142:145], v[194:197], 0
	v_mfma_f32_16x16x32_bf16 v[102:105], v[134:137], v[202:205], 0
	v_mfma_f32_16x16x32_bf16 v[98:101], v[142:145], v[202:205], 0
	v_mfma_f32_16x16x32_bf16 v[86:89], v[134:137], v[216:219], 0
	v_mfma_f32_16x16x32_bf16 v[82:85], v[142:145], v[216:219], 0
	v_mfma_f32_16x16x32_bf16 v[126:129], v[138:141], v[190:193], v[126:129]
	v_mfma_f32_16x16x32_bf16 v[122:125], v[146:149], v[190:193], v[122:125]
	v_mfma_f32_16x16x32_bf16 v[118:121], v[138:141], v[198:201], v[118:121]
	v_mfma_f32_16x16x32_bf16 v[114:117], v[146:149], v[198:201], v[114:117]
	v_mfma_f32_16x16x32_bf16 v[102:105], v[138:141], v[212:215], v[102:105]
	v_mfma_f32_16x16x32_bf16 v[98:101], v[146:149], v[212:215], v[98:101]
	v_mfma_f32_16x16x32_bf16 v[86:89], v[138:141], v[220:223], v[86:89]
	v_mfma_f32_16x16x32_bf16 v[82:85], v[146:149], v[220:223], v[82:85]
	v_mfma_f32_16x16x32_bf16 v[110:113], v[150:153], v[186:189], 0
	v_mfma_f32_16x16x32_bf16 v[106:109], v[158:161], v[186:189], 0
	v_mfma_f32_16x16x32_bf16 v[94:97], v[150:153], v[194:197], 0
	v_mfma_f32_16x16x32_bf16 v[90:93], v[158:161], v[194:197], 0
	v_mfma_f32_16x16x32_bf16 v[78:81], v[150:153], v[202:205], 0
	v_mfma_f32_16x16x32_bf16 v[74:77], v[158:161], v[202:205], 0
	v_mfma_f32_16x16x32_bf16 v[70:73], v[150:153], v[216:219], 0
	v_mfma_f32_16x16x32_bf16 v[66:69], v[158:161], v[216:219], 0
	v_mfma_f32_16x16x32_bf16 v[110:113], v[154:157], v[190:193], v[110:113]
	v_mfma_f32_16x16x32_bf16 v[106:109], v[182:185], v[190:193], v[106:109]
	v_mfma_f32_16x16x32_bf16 v[94:97], v[154:157], v[198:201], v[94:97]
	v_mfma_f32_16x16x32_bf16 v[90:93], v[182:185], v[198:201], v[90:93]
	v_mfma_f32_16x16x32_bf16 v[78:81], v[154:157], v[212:215], v[78:81]
	v_mfma_f32_16x16x32_bf16 v[74:77], v[182:185], v[212:215], v[74:77]
	v_mfma_f32_16x16x32_bf16 v[70:73], v[154:157], v[220:223], v[70:73]
	v_mfma_f32_16x16x32_bf16 v[66:69], v[182:185], v[220:223], v[66:69]
	s_setprio 0
	s_barrier
	s_add_i32 s13, s13, s97
	v_lshl_add_u64 v[224:225], vcc, 0, v[168:169]
	s_mov_b32 m0, s13
	ds_read_b128 v[186:189], v211 offset:16384
	ds_read_b128 v[190:193], v211 offset:17408
	ds_read_b128 v[194:197], v211 offset:18432
	ds_read_b128 v[198:201], v211 offset:19456
	ds_read_b128 v[202:205], v211 offset:20480
	ds_read_b128 v[212:215], v211 offset:21504
	ds_read_b128 v[216:219], v211 offset:22528
	ds_read_b128 v[220:223], v211 offset:23552
	global_load_lds_dwordx4 v[224:225], off
	s_add_i32 m0, s13, 0x2000
	v_lshl_add_u64 v[226:227], vcc, 0, v[172:173]
	s_add_u32 vcc_lo, vcc_lo, s59
	s_addc_u32 vcc_hi, vcc_hi, 0
	s_add_i32 s13, s88, s97
	global_load_lds_dwordx4 v[226:227], off
	v_lshl_add_u64 v[228:229], vcc, 0, v[168:169]
	s_mov_b32 m0, s13
	v_lshl_add_u64 v[230:231], vcc, 0, v[172:173]
	global_load_lds_dwordx4 v[228:229], off
	s_add_i32 m0, s13, 0x2000
	v_lshl_add_u64 v[232:233], s[76:77], 0, v[166:167]
	global_load_lds_dwordx4 v[230:231], off
	s_mov_b32 m0, s80
	v_lshl_add_u64 v[242:243], s[76:77], 0, v[170:171]
	global_load_lds_dwordx4 v[232:233], off
	s_mov_b32 m0, s60
	s_nop 0
	global_load_lds_dwordx4 v[242:243], off
	s_waitcnt vmcnt(8)
	s_waitcnt lgkmcnt(0)
	s_barrier
	s_setprio 1
	s_waitcnt lgkmcnt(0)
	v_mfma_f32_16x16x32_bf16 v[62:65], v[134:137], v[186:189], 0
	v_mfma_f32_16x16x32_bf16 v[58:61], v[142:145], v[186:189], 0
	v_mfma_f32_16x16x32_bf16 v[54:57], v[134:137], v[194:197], 0
	v_mfma_f32_16x16x32_bf16 v[50:53], v[142:145], v[194:197], 0
	v_mfma_f32_16x16x32_bf16 v[38:41], v[134:137], v[202:205], 0
	v_mfma_f32_16x16x32_bf16 v[34:37], v[142:145], v[202:205], 0
	v_mfma_f32_16x16x32_bf16 v[22:25], v[134:137], v[216:219], 0
	v_mfma_f32_16x16x32_bf16 v[18:21], v[142:145], v[216:219], 0
	v_mfma_f32_16x16x32_bf16 v[62:65], v[138:141], v[190:193], v[62:65]
	v_mfma_f32_16x16x32_bf16 v[58:61], v[146:149], v[190:193], v[58:61]
	v_mfma_f32_16x16x32_bf16 v[54:57], v[138:141], v[198:201], v[54:57]
	v_mfma_f32_16x16x32_bf16 v[50:53], v[146:149], v[198:201], v[50:53]
	v_mfma_f32_16x16x32_bf16 v[38:41], v[138:141], v[212:215], v[38:41]
	v_mfma_f32_16x16x32_bf16 v[34:37], v[146:149], v[212:215], v[34:37]
	v_mfma_f32_16x16x32_bf16 v[22:25], v[138:141], v[220:223], v[22:25]
	v_mfma_f32_16x16x32_bf16 v[18:21], v[146:149], v[220:223], v[18:21]
	v_mfma_f32_16x16x32_bf16 v[46:49], v[150:153], v[186:189], 0
	v_mfma_f32_16x16x32_bf16 v[42:45], v[158:161], v[186:189], 0
	v_mfma_f32_16x16x32_bf16 v[30:33], v[150:153], v[194:197], 0
	v_mfma_f32_16x16x32_bf16 v[26:29], v[158:161], v[194:197], 0
	v_mfma_f32_16x16x32_bf16 v[14:17], v[150:153], v[202:205], 0
	v_mfma_f32_16x16x32_bf16 v[10:13], v[158:161], v[202:205], 0
	v_mfma_f32_16x16x32_bf16 v[6:9], v[150:153], v[216:219], 0
	v_mfma_f32_16x16x32_bf16 v[2:5], v[158:161], v[216:219], 0
	v_mfma_f32_16x16x32_bf16 v[46:49], v[154:157], v[190:193], v[46:49]
	v_mfma_f32_16x16x32_bf16 v[42:45], v[182:185], v[190:193], v[42:45]
	v_mfma_f32_16x16x32_bf16 v[30:33], v[154:157], v[198:201], v[30:33]
	v_mfma_f32_16x16x32_bf16 v[26:29], v[182:185], v[198:201], v[26:29]
	v_mfma_f32_16x16x32_bf16 v[14:17], v[154:157], v[212:215], v[14:17]
	v_mfma_f32_16x16x32_bf16 v[10:13], v[182:185], v[212:215], v[10:13]
	v_mfma_f32_16x16x32_bf16 v[6:9], v[154:157], v[220:223], v[6:9]
	v_mfma_f32_16x16x32_bf16 v[2:5], v[182:185], v[220:223], v[2:5]
	s_setprio 0
	s_barrier
	s_branch .Lpeel_mid_rs
.LBB0_388:
	s_add_i32 s12, s12, 2
	s_add_u32 s13, s74, 0x80
	s_addc_u32 vcc_lo, s75, 0
	s_and_b64 s[76:77], s[76:77], exec
	s_cselect_b32 s77, s71, vcc_lo
	s_cselect_b32 s76, s70, s13
	s_cselect_b32 vcc_hi, s45, s73
	s_cselect_b32 vcc_lo, s44, s67
	s_add_i32 s13, 0, 0x10000
	v_add_u32_e32 v1, s13, v208
	s_add_i32 s88, 0, 0x14000
	ds_read_b128 v[134:137], v1
	ds_read_b128 v[138:141], v1 offset:1024
	ds_read_b128 v[142:145], v1 offset:2048
	ds_read_b128 v[146:149], v1 offset:3072
	v_add_u32_e32 v1, s88, v208
	ds_read_b128 v[150:153], v1
	ds_read_b128 v[154:157], v1 offset:1024
	ds_read_b128 v[158:161], v1 offset:2048
	ds_read_b128 v[182:185], v1 offset:3072
	v_lshl_add_u64 v[224:225], s[74:75], 0, v[178:179]
	s_add_i32 m0, s80, 0xc000
	ds_read_b128 v[186:189], v211
	ds_read_b128 v[190:193], v211 offset:1024
	ds_read_b128 v[194:197], v211 offset:2048
	ds_read_b128 v[198:201], v211 offset:3072
	ds_read_b128 v[202:205], v211 offset:4096
	ds_read_b128 v[212:215], v211 offset:5120
	ds_read_b128 v[216:219], v211 offset:6144
	ds_read_b128 v[220:223], v211 offset:7168
	global_load_lds_dwordx4 v[224:225], off
	v_lshl_add_u64 v[224:225], s[74:75], 0, v[180:181]
	s_add_i32 m0, s80, 0xe000
	s_nop 0
	global_load_lds_dwordx4 v[224:225], off
	s_waitcnt vmcnt(8)
	s_waitcnt lgkmcnt(0)
	s_barrier
	s_setprio 1
	s_waitcnt lgkmcnt(0)
	v_mfma_f32_16x16x32_bf16 v[126:129], v[134:137], v[186:189], v[126:129]
	v_mfma_f32_16x16x32_bf16 v[122:125], v[142:145], v[186:189], v[122:125]
	v_mfma_f32_16x16x32_bf16 v[118:121], v[134:137], v[194:197], v[118:121]
	v_mfma_f32_16x16x32_bf16 v[114:117], v[142:145], v[194:197], v[114:117]
	v_mfma_f32_16x16x32_bf16 v[102:105], v[134:137], v[202:205], v[102:105]
	v_mfma_f32_16x16x32_bf16 v[98:101], v[142:145], v[202:205], v[98:101]
	v_mfma_f32_16x16x32_bf16 v[86:89], v[134:137], v[216:219], v[86:89]
	v_mfma_f32_16x16x32_bf16 v[82:85], v[142:145], v[216:219], v[82:85]
	v_mfma_f32_16x16x32_bf16 v[126:129], v[138:141], v[190:193], v[126:129]
	v_mfma_f32_16x16x32_bf16 v[122:125], v[146:149], v[190:193], v[122:125]
	v_mfma_f32_16x16x32_bf16 v[118:121], v[138:141], v[198:201], v[118:121]
	v_mfma_f32_16x16x32_bf16 v[114:117], v[146:149], v[198:201], v[114:117]
	v_mfma_f32_16x16x32_bf16 v[102:105], v[138:141], v[212:215], v[102:105]
	v_mfma_f32_16x16x32_bf16 v[98:101], v[146:149], v[212:215], v[98:101]
	v_mfma_f32_16x16x32_bf16 v[86:89], v[138:141], v[220:223], v[86:89]
	v_mfma_f32_16x16x32_bf16 v[82:85], v[146:149], v[220:223], v[82:85]
	v_mfma_f32_16x16x32_bf16 v[110:113], v[150:153], v[186:189], v[110:113]
	v_mfma_f32_16x16x32_bf16 v[106:109], v[158:161], v[186:189], v[106:109]
	v_mfma_f32_16x16x32_bf16 v[94:97], v[150:153], v[194:197], v[94:97]
	v_mfma_f32_16x16x32_bf16 v[90:93], v[158:161], v[194:197], v[90:93]
	v_mfma_f32_16x16x32_bf16 v[78:81], v[150:153], v[202:205], v[78:81]
	v_mfma_f32_16x16x32_bf16 v[74:77], v[158:161], v[202:205], v[74:77]
	v_mfma_f32_16x16x32_bf16 v[70:73], v[150:153], v[216:219], v[70:73]
	v_mfma_f32_16x16x32_bf16 v[66:69], v[158:161], v[216:219], v[66:69]
	v_mfma_f32_16x16x32_bf16 v[110:113], v[154:157], v[190:193], v[110:113]
	v_mfma_f32_16x16x32_bf16 v[106:109], v[182:185], v[190:193], v[106:109]
	v_mfma_f32_16x16x32_bf16 v[94:97], v[154:157], v[198:201], v[94:97]
	v_mfma_f32_16x16x32_bf16 v[90:93], v[182:185], v[198:201], v[90:93]
	v_mfma_f32_16x16x32_bf16 v[78:81], v[154:157], v[212:215], v[78:81]
	v_mfma_f32_16x16x32_bf16 v[74:77], v[182:185], v[212:215], v[74:77]
	v_mfma_f32_16x16x32_bf16 v[70:73], v[154:157], v[220:223], v[70:73]
	v_mfma_f32_16x16x32_bf16 v[66:69], v[182:185], v[220:223], v[66:69]
	s_setprio 0
	s_barrier
	s_add_i32 s13, s13, s97
	v_lshl_add_u64 v[224:225], vcc, 0, v[168:169]
	s_mov_b32 m0, s13
	ds_read_b128 v[186:189], v211 offset:16384
	ds_read_b128 v[190:193], v211 offset:17408
	ds_read_b128 v[194:197], v211 offset:18432
	ds_read_b128 v[198:201], v211 offset:19456
	ds_read_b128 v[202:205], v211 offset:20480
	ds_read_b128 v[212:215], v211 offset:21504
	ds_read_b128 v[216:219], v211 offset:22528
	ds_read_b128 v[220:223], v211 offset:23552
	global_load_lds_dwordx4 v[224:225], off
	s_add_i32 m0, s13, 0x2000
	v_lshl_add_u64 v[226:227], vcc, 0, v[172:173]
	s_add_u32 vcc_lo, vcc_lo, s59
	s_addc_u32 vcc_hi, vcc_hi, 0
	s_add_i32 s13, s88, s97
	global_load_lds_dwordx4 v[226:227], off
	v_lshl_add_u64 v[228:229], vcc, 0, v[168:169]
	s_mov_b32 m0, s13
	v_lshl_add_u64 v[230:231], vcc, 0, v[172:173]
	global_load_lds_dwordx4 v[228:229], off
	s_add_i32 m0, s13, 0x2000
	v_lshl_add_u64 v[232:233], s[76:77], 0, v[166:167]
	global_load_lds_dwordx4 v[230:231], off
	s_mov_b32 m0, s80
	v_lshl_add_u64 v[242:243], s[76:77], 0, v[170:171]
	global_load_lds_dwordx4 v[232:233], off
	s_mov_b32 m0, s60
	s_nop 0
	global_load_lds_dwordx4 v[242:243], off
	s_waitcnt vmcnt(8)
	s_waitcnt lgkmcnt(0)
	s_barrier
	s_setprio 1
	s_waitcnt lgkmcnt(0)
	v_mfma_f32_16x16x32_bf16 v[62:65], v[134:137], v[186:189], v[62:65]
	v_mfma_f32_16x16x32_bf16 v[58:61], v[142:145], v[186:189], v[58:61]
	v_mfma_f32_16x16x32_bf16 v[54:57], v[134:137], v[194:197], v[54:57]
	v_mfma_f32_16x16x32_bf16 v[50:53], v[142:145], v[194:197], v[50:53]
	v_mfma_f32_16x16x32_bf16 v[38:41], v[134:137], v[202:205], v[38:41]
	v_mfma_f32_16x16x32_bf16 v[34:37], v[142:145], v[202:205], v[34:37]
	v_mfma_f32_16x16x32_bf16 v[22:25], v[134:137], v[216:219], v[22:25]
	v_mfma_f32_16x16x32_bf16 v[18:21], v[142:145], v[216:219], v[18:21]
	v_mfma_f32_16x16x32_bf16 v[62:65], v[138:141], v[190:193], v[62:65]
	v_mfma_f32_16x16x32_bf16 v[58:61], v[146:149], v[190:193], v[58:61]
	v_mfma_f32_16x16x32_bf16 v[54:57], v[138:141], v[198:201], v[54:57]
	v_mfma_f32_16x16x32_bf16 v[50:53], v[146:149], v[198:201], v[50:53]
	v_mfma_f32_16x16x32_bf16 v[38:41], v[138:141], v[212:215], v[38:41]
	v_mfma_f32_16x16x32_bf16 v[34:37], v[146:149], v[212:215], v[34:37]
	v_mfma_f32_16x16x32_bf16 v[22:25], v[138:141], v[220:223], v[22:25]
	v_mfma_f32_16x16x32_bf16 v[18:21], v[146:149], v[220:223], v[18:21]
	v_mfma_f32_16x16x32_bf16 v[46:49], v[150:153], v[186:189], v[46:49]
	v_mfma_f32_16x16x32_bf16 v[42:45], v[158:161], v[186:189], v[42:45]
	v_mfma_f32_16x16x32_bf16 v[30:33], v[150:153], v[194:197], v[30:33]
	v_mfma_f32_16x16x32_bf16 v[26:29], v[158:161], v[194:197], v[26:29]
	v_mfma_f32_16x16x32_bf16 v[14:17], v[150:153], v[202:205], v[14:17]
	v_mfma_f32_16x16x32_bf16 v[10:13], v[158:161], v[202:205], v[10:13]
	v_mfma_f32_16x16x32_bf16 v[6:9], v[150:153], v[216:219], v[6:9]
	v_mfma_f32_16x16x32_bf16 v[2:5], v[158:161], v[216:219], v[2:5]
	v_mfma_f32_16x16x32_bf16 v[46:49], v[154:157], v[190:193], v[46:49]
	v_mfma_f32_16x16x32_bf16 v[42:45], v[182:185], v[190:193], v[42:45]
	v_mfma_f32_16x16x32_bf16 v[30:33], v[154:157], v[198:201], v[30:33]
	v_mfma_f32_16x16x32_bf16 v[26:29], v[182:185], v[198:201], v[26:29]
	v_mfma_f32_16x16x32_bf16 v[14:17], v[154:157], v[212:215], v[14:17]
	v_mfma_f32_16x16x32_bf16 v[10:13], v[182:185], v[212:215], v[10:13]
	v_mfma_f32_16x16x32_bf16 v[6:9], v[154:157], v[220:223], v[6:9]
	v_mfma_f32_16x16x32_bf16 v[2:5], v[182:185], v[220:223], v[2:5]
	s_setprio 0
	s_barrier
.Lpeel_mid_rs:
	s_add_i32 s13, 0, 0x18000
	v_add_u32_e32 v1, s13, v208
	s_add_i32 s88, 0, 0x1c000
	ds_read_b128 v[134:137], v1
	ds_read_b128 v[138:141], v1 offset:1024
	ds_read_b128 v[142:145], v1 offset:2048
	ds_read_b128 v[146:149], v1 offset:3072
	v_add_u32_e32 v1, s88, v208
	ds_read_b128 v[150:153], v1
	ds_read_b128 v[154:157], v1 offset:1024
	ds_read_b128 v[158:161], v1 offset:2048
	ds_read_b128 v[182:185], v1 offset:3072
	s_add_u32 s76, s76, s56
	s_addc_u32 s77, s77, 0
	s_mov_b32 m0, s61
	v_lshl_add_u64 v[244:245], s[76:77], 0, v[166:167]
	ds_read_b128 v[186:189], v211 offset:32768
	ds_read_b128 v[190:193], v211 offset:33792
	ds_read_b128 v[194:197], v211 offset:34816
	ds_read_b128 v[198:201], v211 offset:35840
	ds_read_b128 v[202:205], v211 offset:36864
	ds_read_b128 v[212:215], v211 offset:37888
	ds_read_b128 v[216:219], v211 offset:38912
	ds_read_b128 v[220:223], v211 offset:39936
	global_load_lds_dwordx4 v[244:245], off
	v_lshl_add_u64 v[244:245], s[76:77], 0, v[170:171]
	s_mov_b32 m0, s83
	s_nop 0
	global_load_lds_dwordx4 v[244:245], off
	s_waitcnt vmcnt(8)
	s_waitcnt lgkmcnt(0)
	s_barrier
	s_setprio 1
	s_waitcnt lgkmcnt(0)
	v_mfma_f32_16x16x32_bf16 v[126:129], v[134:137], v[186:189], v[126:129]
	v_mfma_f32_16x16x32_bf16 v[122:125], v[142:145], v[186:189], v[122:125]
	v_mfma_f32_16x16x32_bf16 v[118:121], v[134:137], v[194:197], v[118:121]
	v_mfma_f32_16x16x32_bf16 v[114:117], v[142:145], v[194:197], v[114:117]
	v_mfma_f32_16x16x32_bf16 v[102:105], v[134:137], v[202:205], v[102:105]
	v_mfma_f32_16x16x32_bf16 v[98:101], v[142:145], v[202:205], v[98:101]
	v_mfma_f32_16x16x32_bf16 v[86:89], v[134:137], v[216:219], v[86:89]
	v_mfma_f32_16x16x32_bf16 v[82:85], v[142:145], v[216:219], v[82:85]
	v_mfma_f32_16x16x32_bf16 v[126:129], v[138:141], v[190:193], v[126:129]
	v_mfma_f32_16x16x32_bf16 v[122:125], v[146:149], v[190:193], v[122:125]
	v_mfma_f32_16x16x32_bf16 v[118:121], v[138:141], v[198:201], v[118:121]
	v_mfma_f32_16x16x32_bf16 v[114:117], v[146:149], v[198:201], v[114:117]
	v_mfma_f32_16x16x32_bf16 v[102:105], v[138:141], v[212:215], v[102:105]
	v_mfma_f32_16x16x32_bf16 v[98:101], v[146:149], v[212:215], v[98:101]
	v_mfma_f32_16x16x32_bf16 v[86:89], v[138:141], v[220:223], v[86:89]
	v_mfma_f32_16x16x32_bf16 v[82:85], v[146:149], v[220:223], v[82:85]
	v_mfma_f32_16x16x32_bf16 v[110:113], v[150:153], v[186:189], v[110:113]
	v_mfma_f32_16x16x32_bf16 v[106:109], v[158:161], v[186:189], v[106:109]
	v_mfma_f32_16x16x32_bf16 v[94:97], v[150:153], v[194:197], v[94:97]
	v_mfma_f32_16x16x32_bf16 v[90:93], v[158:161], v[194:197], v[90:93]
	v_mfma_f32_16x16x32_bf16 v[78:81], v[150:153], v[202:205], v[78:81]
	v_mfma_f32_16x16x32_bf16 v[74:77], v[158:161], v[202:205], v[74:77]
	v_mfma_f32_16x16x32_bf16 v[70:73], v[150:153], v[216:219], v[70:73]
	v_mfma_f32_16x16x32_bf16 v[66:69], v[158:161], v[216:219], v[66:69]
	v_mfma_f32_16x16x32_bf16 v[110:113], v[154:157], v[190:193], v[110:113]
	v_mfma_f32_16x16x32_bf16 v[106:109], v[182:185], v[190:193], v[106:109]
	v_mfma_f32_16x16x32_bf16 v[94:97], v[154:157], v[198:201], v[94:97]
	v_mfma_f32_16x16x32_bf16 v[90:93], v[182:185], v[198:201], v[90:93]
	v_mfma_f32_16x16x32_bf16 v[78:81], v[154:157], v[212:215], v[78:81]
	v_mfma_f32_16x16x32_bf16 v[74:77], v[182:185], v[212:215], v[74:77]
	v_mfma_f32_16x16x32_bf16 v[70:73], v[154:157], v[220:223], v[70:73]
	v_mfma_f32_16x16x32_bf16 v[66:69], v[182:185], v[220:223], v[66:69]
	s_setprio 0
	s_barrier
	s_add_i32 s13, s13, s97
	v_lshl_add_u64 v[224:225], v[224:225], 0, s[0:1]
	s_mov_b32 m0, s13
	ds_read_b128 v[186:189], v211 offset:49152
	ds_read_b128 v[190:193], v211 offset:50176
	ds_read_b128 v[194:197], v211 offset:51200
	ds_read_b128 v[198:201], v211 offset:52224
	ds_read_b128 v[202:205], v211 offset:53248
	ds_read_b128 v[212:215], v211 offset:54272
	ds_read_b128 v[216:219], v211 offset:55296
	ds_read_b128 v[220:223], v211 offset:56320
	global_load_lds_dwordx4 v[224:225], off
	v_lshl_add_u64 v[224:225], v[226:227], 0, s[0:1]
	s_add_i32 m0, s13, 0x2000
	s_add_i32 s13, s88, s97
	global_load_lds_dwordx4 v[224:225], off
	v_lshl_add_u64 v[224:225], v[228:229], 0, s[0:1]
	s_mov_b32 m0, s13
	s_nop 0
	global_load_lds_dwordx4 v[224:225], off
	v_lshl_add_u64 v[224:225], v[230:231], 0, s[0:1]
	s_add_i32 m0, s13, 0x2000
	s_nop 0
	global_load_lds_dwordx4 v[224:225], off
	v_lshl_add_u64 v[224:225], v[232:233], 0, s[0:1]
	s_mov_b32 m0, s2
	s_nop 0
	global_load_lds_dwordx4 v[224:225], off
	v_lshl_add_u64 v[224:225], v[242:243], 0, s[0:1]
	s_mov_b32 m0, s86
	s_nop 0
	global_load_lds_dwordx4 v[224:225], off
	s_waitcnt vmcnt(8)
	s_waitcnt lgkmcnt(0)
	s_barrier
	s_setprio 1
	s_waitcnt lgkmcnt(0)
	v_mfma_f32_16x16x32_bf16 v[62:65], v[134:137], v[186:189], v[62:65]
	v_mfma_f32_16x16x32_bf16 v[58:61], v[142:145], v[186:189], v[58:61]
	v_mfma_f32_16x16x32_bf16 v[54:57], v[134:137], v[194:197], v[54:57]
	v_mfma_f32_16x16x32_bf16 v[50:53], v[142:145], v[194:197], v[50:53]
	v_mfma_f32_16x16x32_bf16 v[38:41], v[134:137], v[202:205], v[38:41]
	v_mfma_f32_16x16x32_bf16 v[34:37], v[142:145], v[202:205], v[34:37]
	v_mfma_f32_16x16x32_bf16 v[22:25], v[134:137], v[216:219], v[22:25]
	v_mfma_f32_16x16x32_bf16 v[18:21], v[142:145], v[216:219], v[18:21]
	v_mfma_f32_16x16x32_bf16 v[62:65], v[138:141], v[190:193], v[62:65]
	v_mfma_f32_16x16x32_bf16 v[58:61], v[146:149], v[190:193], v[58:61]
	v_mfma_f32_16x16x32_bf16 v[54:57], v[138:141], v[198:201], v[54:57]
	v_mfma_f32_16x16x32_bf16 v[50:53], v[146:149], v[198:201], v[50:53]
	v_mfma_f32_16x16x32_bf16 v[38:41], v[138:141], v[212:215], v[38:41]
	v_mfma_f32_16x16x32_bf16 v[34:37], v[146:149], v[212:215], v[34:37]
	v_mfma_f32_16x16x32_bf16 v[22:25], v[138:141], v[220:223], v[22:25]
	v_mfma_f32_16x16x32_bf16 v[18:21], v[146:149], v[220:223], v[18:21]
	v_mfma_f32_16x16x32_bf16 v[46:49], v[150:153], v[186:189], v[46:49]
	v_mfma_f32_16x16x32_bf16 v[42:45], v[158:161], v[186:189], v[42:45]
	v_mfma_f32_16x16x32_bf16 v[30:33], v[150:153], v[194:197], v[30:33]
	v_mfma_f32_16x16x32_bf16 v[26:29], v[158:161], v[194:197], v[26:29]
	v_mfma_f32_16x16x32_bf16 v[14:17], v[150:153], v[202:205], v[14:17]
	v_mfma_f32_16x16x32_bf16 v[10:13], v[158:161], v[202:205], v[10:13]
	v_mfma_f32_16x16x32_bf16 v[6:9], v[150:153], v[216:219], v[6:9]
	v_mfma_f32_16x16x32_bf16 v[2:5], v[158:161], v[216:219], v[2:5]
	v_mfma_f32_16x16x32_bf16 v[46:49], v[154:157], v[190:193], v[46:49]
	v_mfma_f32_16x16x32_bf16 v[42:45], v[182:185], v[190:193], v[42:45]
	v_mfma_f32_16x16x32_bf16 v[30:33], v[154:157], v[198:201], v[30:33]
	v_mfma_f32_16x16x32_bf16 v[26:29], v[182:185], v[198:201], v[26:29]
	v_mfma_f32_16x16x32_bf16 v[14:17], v[154:157], v[212:215], v[14:17]
	v_mfma_f32_16x16x32_bf16 v[10:13], v[182:185], v[212:215], v[10:13]
	v_mfma_f32_16x16x32_bf16 v[6:9], v[154:157], v[220:223], v[6:9]
	v_mfma_f32_16x16x32_bf16 v[2:5], v[182:185], v[220:223], v[2:5]
	s_setprio 0
	s_barrier
	s_add_u32 s74, s74, 0x100
	s_addc_u32 s75, s75, 0
	s_add_u32 s67, s67, 0x100
	s_addc_u32 s73, s73, 0
	s_cmp_ge_i32 s12, s90
	s_cbranch_scc1 .LBB0_396

.LBB0_871:
	s_ashr_i32 s55, s54, 31
	s_lshl_b64 s[12:13], s[54:55], 19
	s_add_u32 s56, s8, s12
	s_addc_u32 s57, s9, s13
	s_and_b64 s[12:13], exec, s[42:43]
	s_cselect_b32 s7, s63, s57
	s_cselect_b32 s45, s62, s56
	s_ashr_i32 s53, s52, 31
	s_lshl_b64 s[12:13], s[52:53], 19
	s_add_u32 s58, s24, s12
	s_addc_u32 s59, s25, s13
	s_and_b64 s[12:13], exec, s[42:43]
	s_cselect_b32 s61, s65, s59
	s_cselect_b32 s75, s64, s58
	s_lshl_b64 s[12:13], s[54:55], 11
	v_lshl_add_u64 v[130:131], v[164:165], 0, s[12:13]
	s_lshl_b32 s12, s74, 12
	s_and_b32 s55, s12, 0x1000
	s_lshl_b64 s[12:13], s[52:53], 10
	v_lshl_add_u64 v[132:133], v[166:167], 0, s[12:13]
	v_readlane_b32 s12, v253, 43
	v_readlane_b32 s13, v253, 44
	s_or_b64 s[42:43], s[42:43], s[12:13]
	s_add_u32 s62, s62, 0x40080
	s_addc_u32 s63, s63, 0
	s_add_u32 s12, s64, 0x100
	s_addc_u32 s13, s65, 0
	s_mov_b32 s53, -2
	s_add_i32 s55, s73, s55
	s_mov_b64 s[64:65], -1
	s_add_u32 s66, s62, 0xfffc0080
	s_addc_u32 s67, s63, -1
	s_and_b64 s[64:65], s[64:65], exec
	s_cselect_b32 s67, s67, s7
	s_cselect_b32 s66, s66, s45
	s_cselect_b32 s65, s13, s61
	s_cselect_b32 s64, s12, s75
	s_add_i32 s76, 0, 0x10000
	s_add_i32 s78, 0, 0x14000
	v_add_u32_e32 v146, s76, v169
	v_add_u32_e32 v190, s78, v169
	ds_read_b128 v[134:137], v146
	ds_read_b128 v[138:141], v146 offset:1024
	ds_read_b128 v[142:145], v146 offset:2048
	ds_read_b128 v[146:149], v146 offset:3072
	ds_read_b128 v[150:153], v190
	ds_read_b128 v[182:185], v190 offset:1024
	ds_read_b128 v[186:189], v190 offset:2048
	ds_read_b128 v[190:193], v190 offset:3072
	v_lshl_add_u64 v[226:227], s[62:63], 0, v[178:179]
	s_add_i32 m0, s22, 0xc000
	ds_read_b128 v[194:197], v250
	ds_read_b128 v[198:201], v250 offset:1024
	ds_read_b128 v[202:205], v250 offset:2048
	ds_read_b128 v[206:209], v250 offset:3072
	ds_read_b128 v[210:213], v250 offset:4096
	ds_read_b128 v[214:217], v250 offset:5120
	ds_read_b128 v[218:221], v250 offset:6144
	ds_read_b128 v[222:225], v250 offset:7168
	global_load_lds_dwordx4 v[226:227], off
	v_lshl_add_u64 v[226:227], s[62:63], 0, v[180:181]
	s_add_i32 m0, s22, 0xe000
	s_nop 0
	global_load_lds_dwordx4 v[226:227], off
	s_waitcnt vmcnt(8)
	s_waitcnt lgkmcnt(0)
	s_barrier
	s_setprio 1
	s_waitcnt lgkmcnt(0)
	v_mfma_f32_16x16x32_bf16 v[62:65], v[134:137], v[194:197], 0
	v_mfma_f32_16x16x32_bf16 v[58:61], v[142:145], v[194:197], 0
	v_mfma_f32_16x16x32_bf16 v[54:57], v[134:137], v[202:205], 0
	v_mfma_f32_16x16x32_bf16 v[50:53], v[142:145], v[202:205], 0
	v_mfma_f32_16x16x32_bf16 v[46:49], v[134:137], v[210:213], 0
	v_mfma_f32_16x16x32_bf16 v[42:45], v[142:145], v[210:213], 0
	v_mfma_f32_16x16x32_bf16 v[38:41], v[134:137], v[218:221], 0
	v_mfma_f32_16x16x32_bf16 v[34:37], v[142:145], v[218:221], 0
	v_mfma_f32_16x16x32_bf16 v[62:65], v[138:141], v[198:201], v[62:65]
	v_mfma_f32_16x16x32_bf16 v[58:61], v[146:149], v[198:201], v[58:61]
	v_mfma_f32_16x16x32_bf16 v[54:57], v[138:141], v[206:209], v[54:57]
	v_mfma_f32_16x16x32_bf16 v[50:53], v[146:149], v[206:209], v[50:53]
	v_mfma_f32_16x16x32_bf16 v[46:49], v[138:141], v[214:217], v[46:49]
	v_mfma_f32_16x16x32_bf16 v[42:45], v[146:149], v[214:217], v[42:45]
	v_mfma_f32_16x16x32_bf16 v[38:41], v[138:141], v[222:225], v[38:41]
	v_mfma_f32_16x16x32_bf16 v[34:37], v[146:149], v[222:225], v[34:37]
	v_mfma_f32_16x16x32_bf16 v[126:129], v[150:153], v[194:197], 0
	v_mfma_f32_16x16x32_bf16 v[122:125], v[186:189], v[194:197], 0
	v_mfma_f32_16x16x32_bf16 v[118:121], v[150:153], v[202:205], 0
	v_mfma_f32_16x16x32_bf16 v[114:117], v[186:189], v[202:205], 0
	v_mfma_f32_16x16x32_bf16 v[110:113], v[150:153], v[210:213], 0
	v_mfma_f32_16x16x32_bf16 v[106:109], v[186:189], v[210:213], 0
	v_mfma_f32_16x16x32_bf16 v[102:105], v[150:153], v[218:221], 0
	v_mfma_f32_16x16x32_bf16 v[98:101], v[186:189], v[218:221], 0
	v_mfma_f32_16x16x32_bf16 v[126:129], v[182:185], v[198:201], v[126:129]
	v_mfma_f32_16x16x32_bf16 v[122:125], v[190:193], v[198:201], v[122:125]
	v_mfma_f32_16x16x32_bf16 v[118:121], v[182:185], v[206:209], v[118:121]
	v_mfma_f32_16x16x32_bf16 v[114:117], v[190:193], v[206:209], v[114:117]
	v_mfma_f32_16x16x32_bf16 v[110:113], v[182:185], v[214:217], v[110:113]
	v_mfma_f32_16x16x32_bf16 v[106:109], v[190:193], v[214:217], v[106:109]
	v_mfma_f32_16x16x32_bf16 v[102:105], v[182:185], v[222:225], v[102:105]
	v_mfma_f32_16x16x32_bf16 v[98:101], v[190:193], v[222:225], v[98:101]
	s_setprio 0
	s_barrier
	s_add_i32 s76, s76, s16
	v_lshl_add_u64 v[226:227], s[64:65], 0, v[156:157]
	s_mov_b32 m0, s76
	ds_read_b128 v[194:197], v250 offset:16384
	ds_read_b128 v[198:201], v250 offset:17408
	ds_read_b128 v[202:205], v250 offset:18432
	ds_read_b128 v[206:209], v250 offset:19456
	ds_read_b128 v[210:213], v250 offset:20480
	ds_read_b128 v[214:217], v250 offset:21504
	ds_read_b128 v[218:221], v250 offset:22528
	ds_read_b128 v[222:225], v250 offset:23552
	global_load_lds_dwordx4 v[226:227], off
	s_add_i32 m0, s76, 0x2000
	s_add_u32 s76, s64, 0x40000
	v_lshl_add_u64 v[228:229], s[64:65], 0, v[160:161]
	s_addc_u32 s77, s65, 0
	s_add_i32 s78, s78, s16
	global_load_lds_dwordx4 v[228:229], off
	v_lshl_add_u64 v[230:231], s[76:77], 0, v[156:157]
	s_mov_b32 m0, s78
	v_lshl_add_u64 v[232:233], s[66:67], 0, v[158:159]
	global_load_lds_dwordx4 v[230:231], off
	v_lshl_add_u64 v[230:231], s[76:77], 0, v[160:161]
	s_add_i32 m0, s78, 0x2000
	s_nop 0
	global_load_lds_dwordx4 v[230:231], off
	v_lshl_add_u64 v[230:231], s[66:67], 0, v[154:155]
	s_mov_b32 m0, s22
	s_nop 0
	global_load_lds_dwordx4 v[230:231], off
	s_mov_b32 m0, s23
	s_nop 0
	global_load_lds_dwordx4 v[232:233], off
	s_waitcnt vmcnt(8)
	s_waitcnt lgkmcnt(0)
	s_barrier
	s_setprio 1
	s_waitcnt lgkmcnt(0)
	v_mfma_f32_16x16x32_bf16 v[30:33], v[134:137], v[194:197], 0
	v_mfma_f32_16x16x32_bf16 v[26:29], v[142:145], v[194:197], 0
	v_mfma_f32_16x16x32_bf16 v[22:25], v[134:137], v[202:205], 0
	v_mfma_f32_16x16x32_bf16 v[18:21], v[142:145], v[202:205], 0
	v_mfma_f32_16x16x32_bf16 v[14:17], v[134:137], v[210:213], 0
	v_mfma_f32_16x16x32_bf16 v[10:13], v[142:145], v[210:213], 0
	v_mfma_f32_16x16x32_bf16 v[6:9], v[134:137], v[218:221], 0
	v_mfma_f32_16x16x32_bf16 v[2:5], v[142:145], v[218:221], 0
	v_mfma_f32_16x16x32_bf16 v[30:33], v[138:141], v[198:201], v[30:33]
	v_mfma_f32_16x16x32_bf16 v[26:29], v[146:149], v[198:201], v[26:29]
	v_mfma_f32_16x16x32_bf16 v[22:25], v[138:141], v[206:209], v[22:25]
	v_mfma_f32_16x16x32_bf16 v[18:21], v[146:149], v[206:209], v[18:21]
	v_mfma_f32_16x16x32_bf16 v[14:17], v[138:141], v[214:217], v[14:17]
	v_mfma_f32_16x16x32_bf16 v[10:13], v[146:149], v[214:217], v[10:13]
	v_mfma_f32_16x16x32_bf16 v[6:9], v[138:141], v[222:225], v[6:9]
	v_mfma_f32_16x16x32_bf16 v[2:5], v[146:149], v[222:225], v[2:5]
	v_mfma_f32_16x16x32_bf16 v[94:97], v[150:153], v[194:197], 0
	v_mfma_f32_16x16x32_bf16 v[90:93], v[186:189], v[194:197], 0
	v_mfma_f32_16x16x32_bf16 v[86:89], v[150:153], v[202:205], 0
	v_mfma_f32_16x16x32_bf16 v[82:85], v[186:189], v[202:205], 0
	v_mfma_f32_16x16x32_bf16 v[78:81], v[150:153], v[210:213], 0
	v_mfma_f32_16x16x32_bf16 v[74:77], v[186:189], v[210:213], 0
	v_mfma_f32_16x16x32_bf16 v[70:73], v[150:153], v[218:221], 0
	v_mfma_f32_16x16x32_bf16 v[66:69], v[186:189], v[218:221], 0
	v_mfma_f32_16x16x32_bf16 v[94:97], v[182:185], v[198:201], v[94:97]
	v_mfma_f32_16x16x32_bf16 v[90:93], v[190:193], v[198:201], v[90:93]
	v_mfma_f32_16x16x32_bf16 v[86:89], v[182:185], v[206:209], v[86:89]
	v_mfma_f32_16x16x32_bf16 v[82:85], v[190:193], v[206:209], v[82:85]
	v_mfma_f32_16x16x32_bf16 v[78:81], v[182:185], v[214:217], v[78:81]
	v_mfma_f32_16x16x32_bf16 v[74:77], v[190:193], v[214:217], v[74:77]
	v_mfma_f32_16x16x32_bf16 v[70:73], v[182:185], v[222:225], v[70:73]
	v_mfma_f32_16x16x32_bf16 v[66:69], v[190:193], v[222:225], v[66:69]
	s_setprio 0
	s_barrier
	s_branch .Lpeel_mid_st
.LBB0_872:
	s_add_u32 s66, s62, 0xfffc0080
	s_addc_u32 s67, s63, -1
	s_and_b64 s[64:65], s[64:65], exec
	s_cselect_b32 s67, s67, s7
	s_cselect_b32 s66, s66, s45
	s_cselect_b32 s65, s13, s61
	s_cselect_b32 s64, s12, s75
	s_add_i32 s76, 0, 0x10000
	s_add_i32 s78, 0, 0x14000
	v_add_u32_e32 v146, s76, v169
	v_add_u32_e32 v190, s78, v169
	ds_read_b128 v[134:137], v146
	ds_read_b128 v[138:141], v146 offset:1024
	ds_read_b128 v[142:145], v146 offset:2048
	ds_read_b128 v[146:149], v146 offset:3072
	ds_read_b128 v[150:153], v190
	ds_read_b128 v[182:185], v190 offset:1024
	ds_read_b128 v[186:189], v190 offset:2048
	ds_read_b128 v[190:193], v190 offset:3072
	v_lshl_add_u64 v[226:227], s[62:63], 0, v[178:179]
	s_add_i32 m0, s22, 0xc000
	ds_read_b128 v[194:197], v250
	ds_read_b128 v[198:201], v250 offset:1024
	ds_read_b128 v[202:205], v250 offset:2048
	ds_read_b128 v[206:209], v250 offset:3072
	ds_read_b128 v[210:213], v250 offset:4096
	ds_read_b128 v[214:217], v250 offset:5120
	ds_read_b128 v[218:221], v250 offset:6144
	ds_read_b128 v[222:225], v250 offset:7168
	global_load_lds_dwordx4 v[226:227], off
	v_lshl_add_u64 v[226:227], s[62:63], 0, v[180:181]
	s_add_i32 m0, s22, 0xe000
	s_nop 0
	global_load_lds_dwordx4 v[226:227], off
	s_waitcnt vmcnt(8)
	s_waitcnt lgkmcnt(0)
	s_barrier
	s_setprio 1
	s_waitcnt lgkmcnt(0)
	v_mfma_f32_16x16x32_bf16 v[62:65], v[134:137], v[194:197], v[62:65]
	v_mfma_f32_16x16x32_bf16 v[58:61], v[142:145], v[194:197], v[58:61]
	v_mfma_f32_16x16x32_bf16 v[54:57], v[134:137], v[202:205], v[54:57]
	v_mfma_f32_16x16x32_bf16 v[50:53], v[142:145], v[202:205], v[50:53]
	v_mfma_f32_16x16x32_bf16 v[46:49], v[134:137], v[210:213], v[46:49]
	v_mfma_f32_16x16x32_bf16 v[42:45], v[142:145], v[210:213], v[42:45]
	v_mfma_f32_16x16x32_bf16 v[38:41], v[134:137], v[218:221], v[38:41]
	v_mfma_f32_16x16x32_bf16 v[34:37], v[142:145], v[218:221], v[34:37]
	v_mfma_f32_16x16x32_bf16 v[62:65], v[138:141], v[198:201], v[62:65]
	v_mfma_f32_16x16x32_bf16 v[58:61], v[146:149], v[198:201], v[58:61]
	v_mfma_f32_16x16x32_bf16 v[54:57], v[138:141], v[206:209], v[54:57]
	v_mfma_f32_16x16x32_bf16 v[50:53], v[146:149], v[206:209], v[50:53]
	v_mfma_f32_16x16x32_bf16 v[46:49], v[138:141], v[214:217], v[46:49]
	v_mfma_f32_16x16x32_bf16 v[42:45], v[146:149], v[214:217], v[42:45]
	v_mfma_f32_16x16x32_bf16 v[38:41], v[138:141], v[222:225], v[38:41]
	v_mfma_f32_16x16x32_bf16 v[34:37], v[146:149], v[222:225], v[34:37]
	v_mfma_f32_16x16x32_bf16 v[126:129], v[150:153], v[194:197], v[126:129]
	v_mfma_f32_16x16x32_bf16 v[122:125], v[186:189], v[194:197], v[122:125]
	v_mfma_f32_16x16x32_bf16 v[118:121], v[150:153], v[202:205], v[118:121]
	v_mfma_f32_16x16x32_bf16 v[114:117], v[186:189], v[202:205], v[114:117]
	v_mfma_f32_16x16x32_bf16 v[110:113], v[150:153], v[210:213], v[110:113]
	v_mfma_f32_16x16x32_bf16 v[106:109], v[186:189], v[210:213], v[106:109]
	v_mfma_f32_16x16x32_bf16 v[102:105], v[150:153], v[218:221], v[102:105]
	v_mfma_f32_16x16x32_bf16 v[98:101], v[186:189], v[218:221], v[98:101]
	v_mfma_f32_16x16x32_bf16 v[126:129], v[182:185], v[198:201], v[126:129]
	v_mfma_f32_16x16x32_bf16 v[122:125], v[190:193], v[198:201], v[122:125]
	v_mfma_f32_16x16x32_bf16 v[118:121], v[182:185], v[206:209], v[118:121]
	v_mfma_f32_16x16x32_bf16 v[114:117], v[190:193], v[206:209], v[114:117]
	v_mfma_f32_16x16x32_bf16 v[110:113], v[182:185], v[214:217], v[110:113]
	v_mfma_f32_16x16x32_bf16 v[106:109], v[190:193], v[214:217], v[106:109]
	v_mfma_f32_16x16x32_bf16 v[102:105], v[182:185], v[222:225], v[102:105]
	v_mfma_f32_16x16x32_bf16 v[98:101], v[190:193], v[222:225], v[98:101]
	s_setprio 0
	s_barrier
	s_add_i32 s76, s76, s16
	v_lshl_add_u64 v[226:227], s[64:65], 0, v[156:157]
	s_mov_b32 m0, s76
	ds_read_b128 v[194:197], v250 offset:16384
	ds_read_b128 v[198:201], v250 offset:17408
	ds_read_b128 v[202:205], v250 offset:18432
	ds_read_b128 v[206:209], v250 offset:19456
	ds_read_b128 v[210:213], v250 offset:20480
	ds_read_b128 v[214:217], v250 offset:21504
	ds_read_b128 v[218:221], v250 offset:22528
	ds_read_b128 v[222:225], v250 offset:23552
	global_load_lds_dwordx4 v[226:227], off
	s_add_i32 m0, s76, 0x2000
	s_add_u32 s76, s64, 0x40000
	v_lshl_add_u64 v[228:229], s[64:65], 0, v[160:161]
	s_addc_u32 s77, s65, 0
	s_add_i32 s78, s78, s16
	global_load_lds_dwordx4 v[228:229], off
	v_lshl_add_u64 v[230:231], s[76:77], 0, v[156:157]
	s_mov_b32 m0, s78
	v_lshl_add_u64 v[232:233], s[66:67], 0, v[158:159]
	global_load_lds_dwordx4 v[230:231], off
	v_lshl_add_u64 v[230:231], s[76:77], 0, v[160:161]
	s_add_i32 m0, s78, 0x2000
	s_nop 0
	global_load_lds_dwordx4 v[230:231], off
	v_lshl_add_u64 v[230:231], s[66:67], 0, v[154:155]
	s_mov_b32 m0, s22
	s_nop 0
	global_load_lds_dwordx4 v[230:231], off
	s_mov_b32 m0, s23
	s_nop 0
	global_load_lds_dwordx4 v[232:233], off
	s_waitcnt vmcnt(8)
	s_waitcnt lgkmcnt(0)
	s_barrier
	s_setprio 1
	s_waitcnt lgkmcnt(0)
	v_mfma_f32_16x16x32_bf16 v[30:33], v[134:137], v[194:197], v[30:33]
	v_mfma_f32_16x16x32_bf16 v[26:29], v[142:145], v[194:197], v[26:29]
	v_mfma_f32_16x16x32_bf16 v[22:25], v[134:137], v[202:205], v[22:25]
	v_mfma_f32_16x16x32_bf16 v[18:21], v[142:145], v[202:205], v[18:21]
	v_mfma_f32_16x16x32_bf16 v[14:17], v[134:137], v[210:213], v[14:17]
	v_mfma_f32_16x16x32_bf16 v[10:13], v[142:145], v[210:213], v[10:13]
	v_mfma_f32_16x16x32_bf16 v[6:9], v[134:137], v[218:221], v[6:9]
	v_mfma_f32_16x16x32_bf16 v[2:5], v[142:145], v[218:221], v[2:5]
	v_mfma_f32_16x16x32_bf16 v[30:33], v[138:141], v[198:201], v[30:33]
	v_mfma_f32_16x16x32_bf16 v[26:29], v[146:149], v[198:201], v[26:29]
	v_mfma_f32_16x16x32_bf16 v[22:25], v[138:141], v[206:209], v[22:25]
	v_mfma_f32_16x16x32_bf16 v[18:21], v[146:149], v[206:209], v[18:21]
	v_mfma_f32_16x16x32_bf16 v[14:17], v[138:141], v[214:217], v[14:17]
	v_mfma_f32_16x16x32_bf16 v[10:13], v[146:149], v[214:217], v[10:13]
	v_mfma_f32_16x16x32_bf16 v[6:9], v[138:141], v[222:225], v[6:9]
	v_mfma_f32_16x16x32_bf16 v[2:5], v[146:149], v[222:225], v[2:5]
	v_mfma_f32_16x16x32_bf16 v[94:97], v[150:153], v[194:197], v[94:97]
	v_mfma_f32_16x16x32_bf16 v[90:93], v[186:189], v[194:197], v[90:93]
	v_mfma_f32_16x16x32_bf16 v[86:89], v[150:153], v[202:205], v[86:89]
	v_mfma_f32_16x16x32_bf16 v[82:85], v[186:189], v[202:205], v[82:85]
	v_mfma_f32_16x16x32_bf16 v[78:81], v[150:153], v[210:213], v[78:81]
	v_mfma_f32_16x16x32_bf16 v[74:77], v[186:189], v[210:213], v[74:77]
	v_mfma_f32_16x16x32_bf16 v[70:73], v[150:153], v[218:221], v[70:73]
	v_mfma_f32_16x16x32_bf16 v[66:69], v[186:189], v[218:221], v[66:69]
	v_mfma_f32_16x16x32_bf16 v[94:97], v[182:185], v[198:201], v[94:97]
	v_mfma_f32_16x16x32_bf16 v[90:93], v[190:193], v[198:201], v[90:93]
	v_mfma_f32_16x16x32_bf16 v[86:89], v[182:185], v[206:209], v[86:89]
	v_mfma_f32_16x16x32_bf16 v[82:85], v[190:193], v[206:209], v[82:85]
	v_mfma_f32_16x16x32_bf16 v[78:81], v[182:185], v[214:217], v[78:81]
	v_mfma_f32_16x16x32_bf16 v[74:77], v[190:193], v[214:217], v[74:77]
	v_mfma_f32_16x16x32_bf16 v[70:73], v[182:185], v[222:225], v[70:73]
	v_mfma_f32_16x16x32_bf16 v[66:69], v[190:193], v[222:225], v[66:69]
	s_setprio 0
	s_barrier
.Lpeel_mid_st:
	s_add_i32 s76, 0, 0x18000
	s_add_i32 s77, 0, 0x1c000
	v_add_u32_e32 v146, s76, v169
	v_add_u32_e32 v190, s77, v169
	ds_read_b128 v[134:137], v146
	ds_read_b128 v[138:141], v146 offset:1024
	ds_read_b128 v[142:145], v146 offset:2048
	ds_read_b128 v[146:149], v146 offset:3072
	ds_read_b128 v[150:153], v190
	ds_read_b128 v[182:185], v190 offset:1024
	ds_read_b128 v[186:189], v190 offset:2048
	ds_read_b128 v[190:193], v190 offset:3072
	s_add_u32 s66, s66, 0x40000
	s_addc_u32 s67, s67, 0
	s_mov_b32 m0, s37
	v_lshl_add_u64 v[242:243], s[66:67], 0, v[154:155]
	ds_read_b128 v[194:197], v250 offset:32768
	ds_read_b128 v[198:201], v250 offset:33792
	ds_read_b128 v[202:205], v250 offset:34816
	ds_read_b128 v[206:209], v250 offset:35840
	ds_read_b128 v[210:213], v250 offset:36864
	ds_read_b128 v[214:217], v250 offset:37888
	ds_read_b128 v[218:221], v250 offset:38912
	ds_read_b128 v[222:225], v250 offset:39936
	global_load_lds_dwordx4 v[242:243], off
	v_lshl_add_u64 v[242:243], s[66:67], 0, v[158:159]
	s_mov_b32 m0, s68
	s_nop 0
	global_load_lds_dwordx4 v[242:243], off
	s_waitcnt vmcnt(8)
	s_waitcnt lgkmcnt(0)
	s_barrier
	s_setprio 1
	s_waitcnt lgkmcnt(0)
	v_mfma_f32_16x16x32_bf16 v[62:65], v[134:137], v[194:197], v[62:65]
	v_mfma_f32_16x16x32_bf16 v[58:61], v[142:145], v[194:197], v[58:61]
	v_mfma_f32_16x16x32_bf16 v[54:57], v[134:137], v[202:205], v[54:57]
	v_mfma_f32_16x16x32_bf16 v[50:53], v[142:145], v[202:205], v[50:53]
	v_mfma_f32_16x16x32_bf16 v[46:49], v[134:137], v[210:213], v[46:49]
	v_mfma_f32_16x16x32_bf16 v[42:45], v[142:145], v[210:213], v[42:45]
	v_mfma_f32_16x16x32_bf16 v[38:41], v[134:137], v[218:221], v[38:41]
	v_mfma_f32_16x16x32_bf16 v[34:37], v[142:145], v[218:221], v[34:37]
	v_mfma_f32_16x16x32_bf16 v[62:65], v[138:141], v[198:201], v[62:65]
	v_mfma_f32_16x16x32_bf16 v[58:61], v[146:149], v[198:201], v[58:61]
	v_mfma_f32_16x16x32_bf16 v[54:57], v[138:141], v[206:209], v[54:57]
	v_mfma_f32_16x16x32_bf16 v[50:53], v[146:149], v[206:209], v[50:53]
	v_mfma_f32_16x16x32_bf16 v[46:49], v[138:141], v[214:217], v[46:49]
	v_mfma_f32_16x16x32_bf16 v[42:45], v[146:149], v[214:217], v[42:45]
	v_mfma_f32_16x16x32_bf16 v[38:41], v[138:141], v[222:225], v[38:41]
	v_mfma_f32_16x16x32_bf16 v[34:37], v[146:149], v[222:225], v[34:37]
	v_mfma_f32_16x16x32_bf16 v[126:129], v[150:153], v[194:197], v[126:129]
	v_mfma_f32_16x16x32_bf16 v[122:125], v[186:189], v[194:197], v[122:125]
	v_mfma_f32_16x16x32_bf16 v[118:121], v[150:153], v[202:205], v[118:121]
	v_mfma_f32_16x16x32_bf16 v[114:117], v[186:189], v[202:205], v[114:117]
	v_mfma_f32_16x16x32_bf16 v[110:113], v[150:153], v[210:213], v[110:113]
	v_mfma_f32_16x16x32_bf16 v[106:109], v[186:189], v[210:213], v[106:109]
	v_mfma_f32_16x16x32_bf16 v[102:105], v[150:153], v[218:221], v[102:105]
	v_mfma_f32_16x16x32_bf16 v[98:101], v[186:189], v[218:221], v[98:101]
	v_mfma_f32_16x16x32_bf16 v[126:129], v[182:185], v[198:201], v[126:129]
	v_mfma_f32_16x16x32_bf16 v[122:125], v[190:193], v[198:201], v[122:125]
	v_mfma_f32_16x16x32_bf16 v[118:121], v[182:185], v[206:209], v[118:121]
	v_mfma_f32_16x16x32_bf16 v[114:117], v[190:193], v[206:209], v[114:117]
	v_mfma_f32_16x16x32_bf16 v[110:113], v[182:185], v[214:217], v[110:113]
	v_mfma_f32_16x16x32_bf16 v[106:109], v[190:193], v[214:217], v[106:109]
	v_mfma_f32_16x16x32_bf16 v[102:105], v[182:185], v[222:225], v[102:105]
	v_mfma_f32_16x16x32_bf16 v[98:101], v[190:193], v[222:225], v[98:101]
	s_setprio 0
	s_barrier
	s_add_i32 s66, s76, s16
	v_lshl_add_u64 v[226:227], v[226:227], 0, s[0:1]
	s_mov_b32 m0, s66
	ds_read_b128 v[194:197], v250 offset:49152
	ds_read_b128 v[198:201], v250 offset:50176
	ds_read_b128 v[202:205], v250 offset:51200
	ds_read_b128 v[206:209], v250 offset:52224
	ds_read_b128 v[210:213], v250 offset:53248
	ds_read_b128 v[214:217], v250 offset:54272
	ds_read_b128 v[218:221], v250 offset:55296
	ds_read_b128 v[222:225], v250 offset:56320
	global_load_lds_dwordx4 v[226:227], off
	s_add_i32 m0, s66, 0x2000
	s_add_u32 s64, s64, 0x40080
	v_lshl_add_u64 v[226:227], v[228:229], 0, s[0:1]
	s_addc_u32 s65, s65, 0
	s_add_i32 s66, s77, s16
	global_load_lds_dwordx4 v[226:227], off
	v_lshl_add_u64 v[226:227], s[64:65], 0, v[156:157]
	s_mov_b32 m0, s66
	s_nop 0
	global_load_lds_dwordx4 v[226:227], off
	v_lshl_add_u64 v[226:227], s[64:65], 0, v[160:161]
	s_add_i32 m0, s66, 0x2000
	s_nop 0
	global_load_lds_dwordx4 v[226:227], off
	v_lshl_add_u64 v[226:227], v[230:231], 0, s[0:1]
	s_mov_b32 m0, s71
	s_nop 0
	global_load_lds_dwordx4 v[226:227], off
	v_lshl_add_u64 v[226:227], v[232:233], 0, s[0:1]
	s_mov_b32 m0, s72
	s_nop 0
	global_load_lds_dwordx4 v[226:227], off
	s_waitcnt vmcnt(8)
	s_waitcnt lgkmcnt(0)
	s_barrier
	s_setprio 1
	s_waitcnt lgkmcnt(0)
	v_mfma_f32_16x16x32_bf16 v[30:33], v[134:137], v[194:197], v[30:33]
	v_mfma_f32_16x16x32_bf16 v[26:29], v[142:145], v[194:197], v[26:29]
	v_mfma_f32_16x16x32_bf16 v[22:25], v[134:137], v[202:205], v[22:25]
	v_mfma_f32_16x16x32_bf16 v[18:21], v[142:145], v[202:205], v[18:21]
	v_mfma_f32_16x16x32_bf16 v[14:17], v[134:137], v[210:213], v[14:17]
	v_mfma_f32_16x16x32_bf16 v[10:13], v[142:145], v[210:213], v[10:13]
	v_mfma_f32_16x16x32_bf16 v[6:9], v[134:137], v[218:221], v[6:9]
	v_mfma_f32_16x16x32_bf16 v[2:5], v[142:145], v[218:221], v[2:5]
	v_mfma_f32_16x16x32_bf16 v[30:33], v[138:141], v[198:201], v[30:33]
	v_mfma_f32_16x16x32_bf16 v[26:29], v[146:149], v[198:201], v[26:29]
	v_mfma_f32_16x16x32_bf16 v[22:25], v[138:141], v[206:209], v[22:25]
	v_mfma_f32_16x16x32_bf16 v[18:21], v[146:149], v[206:209], v[18:21]
	v_mfma_f32_16x16x32_bf16 v[14:17], v[138:141], v[214:217], v[14:17]
	v_mfma_f32_16x16x32_bf16 v[10:13], v[146:149], v[214:217], v[10:13]
	v_mfma_f32_16x16x32_bf16 v[6:9], v[138:141], v[222:225], v[6:9]
	v_mfma_f32_16x16x32_bf16 v[2:5], v[146:149], v[222:225], v[2:5]
	v_mfma_f32_16x16x32_bf16 v[94:97], v[150:153], v[194:197], v[94:97]
	v_mfma_f32_16x16x32_bf16 v[90:93], v[186:189], v[194:197], v[90:93]
	v_mfma_f32_16x16x32_bf16 v[86:89], v[150:153], v[202:205], v[86:89]
	v_mfma_f32_16x16x32_bf16 v[82:85], v[186:189], v[202:205], v[82:85]
	v_mfma_f32_16x16x32_bf16 v[78:81], v[150:153], v[210:213], v[78:81]
	v_mfma_f32_16x16x32_bf16 v[74:77], v[186:189], v[210:213], v[74:77]
	v_mfma_f32_16x16x32_bf16 v[70:73], v[150:153], v[218:221], v[70:73]
	v_mfma_f32_16x16x32_bf16 v[66:69], v[186:189], v[218:221], v[66:69]
	v_mfma_f32_16x16x32_bf16 v[94:97], v[182:185], v[198:201], v[94:97]
	v_mfma_f32_16x16x32_bf16 v[90:93], v[190:193], v[198:201], v[90:93]
	v_mfma_f32_16x16x32_bf16 v[86:89], v[182:185], v[206:209], v[86:89]
	v_mfma_f32_16x16x32_bf16 v[82:85], v[190:193], v[206:209], v[82:85]
	v_mfma_f32_16x16x32_bf16 v[78:81], v[182:185], v[214:217], v[78:81]
	v_mfma_f32_16x16x32_bf16 v[74:77], v[190:193], v[214:217], v[74:77]
	v_mfma_f32_16x16x32_bf16 v[70:73], v[182:185], v[222:225], v[70:73]
	v_mfma_f32_16x16x32_bf16 v[66:69], v[190:193], v[222:225], v[66:69]
	s_setprio 0
	s_barrier
	s_add_i32 s53, s53, 2
	s_add_u32 s62, s62, 0x100
	s_addc_u32 s63, s63, 0
	s_add_u32 s12, s12, 0x100
	s_addc_u32 s13, s13, 0
	s_cmp_gt_u32 s53, 13
	s_cbranch_scc1 .LBB0_875
